# G0 next-tile pre-staging (k-steps 0,1 DMA issued before the epilogue) + hand-written tile setup
# speedup vs baseline: 1.0704x; 1.0078x over previous
; template <int MODE>
; DI void gemm_phase(const Params& p, int layer, int hf, unsigned char* shmc, int tid) {
;     ...
;   const int wid = tid >> 6, lane = tid & 63, wr = wid >> 2, wc = wid & 3, fr = lane & 15, fq = lane >> 4;
;   constexpr int BK2 = 32, NST = 4;
;   const int nt = K / BK2;
;   int la0, lb0;
;   { const int ob = fr * 64 + fq * 16, sw = ob ^ (((ob >> 9) & 1) << 5); la0 = (wr * 4) * 1024 + sw; lb0 = (wc * 2) * 1024 + sw; }
;   Unit u, un;
;   bool have = unit_next(0, gridDim.x, blockIdx.x, nM, nN, u), pre = false;
;   for (int ui = 0; have; ++ui) {
;     const bool have_n = unit_next(ui + 1, gridDim.x, blockIdx.x, nM, nN, un);
;     const int brow = u.pm * BM, bcol = u.pn * BM;
.LBB0_151:
	v_readlane_b32 s0, v253, 24
	v_readlane_b32 s1, v253, 25
	v_mov_b32_e32 v172, v163
	s_andn2_b64 vcc, exec, s[0:1]
	s_cbranch_vccnz .LBB0_181
	s_mov_b32 s28, 0
	s_lshl_b32 s0, s12, 25
	v_readlane_b32 s4, v252, 48
	v_bfe_u32 v1, v172, 6, 2
	v_bfe_u32 v3, v172, 4, 2
	s_add_u32 s2, s4, s0
	v_lshlrev_b32_e32 v5, 4, v3
	v_lshlrev_b32_e32 v179, 11, v1
	v_cmp_eq_u32_e64 s[0:1], 0, v1
	v_lshlrev_b32_e32 v1, 6, v1
	v_lshlrev_b32_e32 v3, 3, v3
	v_readlane_b32 s6, v253, 62
	v_and_b32_e32 v2, 15, v172
	v_lshlrev_b32_e32 v7, 2, v172
	v_add3_u32 v1, s6, v1, v3
	v_lshlrev_b32_e32 v3, 4, v172
	v_ashrrev_i32_e32 v0, 8, v172
	v_lshlrev_b32_e32 v4, 6, v2
	v_and_b32_e32 v8, 32, v7
	v_and_b32_e32 v160, 0x1f0, v3
	v_or_b32_e32 v6, v5, v4
	v_bitop3_b32 v164, v5, v8, v4 bitop3:0x36
	v_lshlrev_b32_e32 v4, 12, v0
	v_lshl_or_b32 v0, v0, 6, v2
	v_add_u32_e32 v3, s6, v160
	s_movk_i32 s6, 0x90
	v_readlane_b32 s5, v252, 49
	v_bitop3_b32 v178, v6, v4, v8 bitop3:0xde
	v_ashrrev_i32_e32 v180, 5, v172
	v_mul_lo_u32 v4, v0, s6
	s_movk_i32 s6, 0x210
	s_mov_b32 s13, s3
	s_addc_u32 s20, s5, 0
	v_add_u32_e32 v2, 32, v5
	s_lshl_b32 s22, s12, 14
	v_mul_lo_u32 v5, v180, s6
	v_mul_lo_u32 v0, v0, s6
	s_lshl_b64 s[6:7], s[12:13], 25
	s_movk_i32 s4, 0x1800
	s_add_u32 s13, s38, s6
	v_ashrrev_i32_e32 v173, 31, v172
	s_mov_b32 s21, 0
	v_cmp_gt_i32_e64 s[4:5], s4, v172
	v_lshl_add_u64 v[174:175], s[38:39], 0, v[160:161]
	v_add_u32_e32 v181, 16, v180
	v_add_u32_e32 v182, 32, v180
	v_add_u32_e32 v183, 48, v180
	v_add_u32_e32 v184, 64, v180
	v_add_u32_e32 v185, 0x50, v180
	v_add_u32_e32 v186, 0x60, v180
	v_add_u32_e32 v187, 0x70, v180
	s_addc_u32 s23, s39, s7
	v_lshl_add_u64 v[176:177], v[172:173], 2, s[62:63]
	v_add_u32_e32 v173, 32, v7
	v_add_u32_e32 v188, v2, v4
	v_add_u32_e32 v189, v1, v0
	v_add_u32_e32 v190, v3, v5
	v_readlane_b32 s27, v253, 43
	v_readlane_b32 s26, v253, 45
	s_branch .LBB0_154

; #define WAIT_V(n) asm volatile("s_waitcnt vmcnt(" #n ")" ::: "memory")
; #define BAR __builtin_amdgcn_s_barrier()
; template <int MODE>
; DI void gemm_phase(const Params& p, int layer, int hf, unsigned char* shmc, int tid) {
;     ...
; #pragma unroll
;     for (int a = 0; a < 2; ++a)
; #pragma unroll
;       for (int b = 0; b < 2; ++b)
; #pragma unroll
;         for (int m = 0; m < 4; ++m)
; #pragma unroll
;           for (int n = 0; n < 2; ++n) acc[a][b][m][n] = (f32x4){0.f, 0.f, 0.f, 0.f};
;     const bf16_t* gA = (MODE == 0) ? A + (size_t)(brow >> 7) * nt * 4096 : A + (size_t)brow * lda; const bf16_t* gB = Bt + (size_t)(bcol >> 7) * nt * 4096;
;     ...
;     if (!pre) { STAGE_ALL(0, 0); STAGE_ALL(1, 1); }
;     STAGE_ALL(2, 2);
;     for (int kt = 0; kt < nt; ++kt) {
;       const int rem = nt - 1 - kt;
;       if (rem >= 2) WAIT_V(8); else if (rem == 1) WAIT_V(4); else WAIT_V(0);
;       BAR;
.LBB0_156:
	v_lshlrev_b32_e32 v160, 4, v172
	s_nop 0
	v_readfirstlane_b32 s29, v160
	s_nop 3
	s_add_i32 s29, s29, 32
	s_cmp_lg_u32 s28, 0
	s_cbranch_scc1 .Lg0_havepre
	s_lshl_b32 s16, s27, 1
	s_ashr_i32 s17, s16, 31
	s_lshl_b64 s[16:17], s[16:17], 18
	s_add_u32 s98, s13, s16
	s_addc_u32 s99, s23, s17
	s_add_u32 s98, s98, 0xd000000
	s_addc_u32 s99, s99, 0
	s_lshl_b32 s16, s26, 1
	s_ashr_i32 s17, s16, 31
	s_lshl_b64 s[16:17], s[16:17], 18
	v_readlane_b32 s100, v254, 7
	v_readlane_b32 s101, v254, 8
	s_nop 3
	s_add_u32 s100, s100, s16
	s_addc_u32 s101, s101, s17
	s_add_u32 s100, s100, 0x11000000
	s_addc_u32 s101, s101, 0
	s_mov_b32 m0, s29
	s_add_u32 s18, s98, 0x40000
	s_addc_u32 s19, s99, 0
	global_load_lds_dwordx4 v160, s[98:99]
	s_add_u32 m0, s29, 0x4000
	s_add_u32 s16, s100, 0x40000
	s_addc_u32 s17, s101, 0
	global_load_lds_dwordx4 v160, s[100:101]
	s_add_u32 m0, s29, 0x2000
	s_add_u32 s98, s98, 0x2000
	s_addc_u32 s99, s99, 0
	global_load_lds_dwordx4 v160, s[18:19]
	s_add_u32 m0, s29, 0x6000
	s_add_u32 s100, s100, 0x2000
	s_addc_u32 s101, s101, 0
	global_load_lds_dwordx4 v160, s[16:17]
	s_add_u32 m0, s29, 0x8000
	s_add_u32 s18, s98, 0x40000
	s_addc_u32 s19, s99, 0
	global_load_lds_dwordx4 v160, s[98:99]
	s_add_u32 m0, s29, 0xc000
	s_add_u32 s16, s100, 0x40000
	s_addc_u32 s17, s101, 0
	global_load_lds_dwordx4 v160, s[100:101]
	s_add_u32 m0, s29, 0xa000
	s_add_u32 s98, s98, 0x2000
	s_addc_u32 s99, s99, 0
	global_load_lds_dwordx4 v160, s[18:19]
	s_add_u32 m0, s29, 0xe000
	s_add_u32 s100, s100, 0x2000
	s_addc_u32 s101, s101, 0
	global_load_lds_dwordx4 v160, s[16:17]
.Lg0_havepre:
	s_add_u32 m0, s29, 0x10000
	s_add_u32 s18, s98, 0x40000
	s_addc_u32 s19, s99, 0
	global_load_lds_dwordx4 v160, s[98:99]
	s_add_u32 m0, s29, 0x14000
	s_add_u32 s16, s100, 0x40000
	s_addc_u32 s17, s101, 0
	global_load_lds_dwordx4 v160, s[100:101]
	s_add_u32 m0, s29, 0x12000
	s_add_u32 s98, s98, 0x2000
	s_addc_u32 s99, s99, 0
	global_load_lds_dwordx4 v160, s[18:19]
	s_add_u32 m0, s29, 0x16000
	s_add_u32 s100, s100, 0x2000
	s_addc_u32 s101, s101, 0
	global_load_lds_dwordx4 v160, s[16:17]
	v_mov_b32_e32 v0, 0
	s_addc_u32 s15, s15, s17
	s_mov_b64 s[16:17], 0
	v_mov_b32_e32 v1, v0
	v_mov_b32_e32 v2, v0
	v_mov_b32_e32 v3, v0
	v_mov_b32_e32 v4, v0
	v_mov_b32_e32 v5, v0
	v_mov_b32_e32 v6, v0
	v_mov_b32_e32 v7, v0
	v_mov_b32_e32 v24, v0
	v_mov_b32_e32 v25, v0
	v_mov_b32_e32 v26, v0
	v_mov_b32_e32 v27, v0
	v_mov_b32_e32 v36, v0
	v_mov_b32_e32 v37, v0
	v_mov_b32_e32 v38, v0
	v_mov_b32_e32 v39, v0
	v_mov_b32_e32 v56, v0
	v_mov_b32_e32 v57, v0
	v_mov_b32_e32 v58, v0
	v_mov_b32_e32 v59, v0
	v_mov_b32_e32 v68, v0
	v_mov_b32_e32 v69, v0
	v_mov_b32_e32 v70, v0
	v_mov_b32_e32 v71, v0
	v_mov_b32_e32 v72, v0
	v_mov_b32_e32 v73, v0
	v_mov_b32_e32 v74, v0
	v_mov_b32_e32 v75, v0
	v_mov_b32_e32 v80, v0
	v_mov_b32_e32 v81, v0
	v_mov_b32_e32 v82, v0
	v_mov_b32_e32 v83, v0
	v_mov_b32_e32 v88, v0
	v_mov_b32_e32 v89, v0
	v_mov_b32_e32 v90, v0
	v_mov_b32_e32 v91, v0
	v_mov_b32_e32 v96, v0
	v_mov_b32_e32 v97, v0
	v_mov_b32_e32 v98, v0
	v_mov_b32_e32 v99, v0
	v_mov_b32_e32 v104, v0
	v_mov_b32_e32 v105, v0
	v_mov_b32_e32 v106, v0
	v_mov_b32_e32 v107, v0
	v_mov_b32_e32 v112, v0
	v_mov_b32_e32 v113, v0
	v_mov_b32_e32 v114, v0
	v_mov_b32_e32 v115, v0
	v_mov_b32_e32 v76, v0
	v_mov_b32_e32 v77, v0
	v_mov_b32_e32 v78, v0
	v_mov_b32_e32 v79, v0
	v_mov_b32_e32 v84, v0
	v_mov_b32_e32 v85, v0
	v_mov_b32_e32 v86, v0
	v_mov_b32_e32 v87, v0
	v_mov_b32_e32 v92, v0
	v_mov_b32_e32 v93, v0
	v_mov_b32_e32 v94, v0
	v_mov_b32_e32 v95, v0
	v_mov_b32_e32 v100, v0
	v_mov_b32_e32 v101, v0
	v_mov_b32_e32 v102, v0
	v_mov_b32_e32 v103, v0
	v_mov_b32_e32 v108, v0
	v_mov_b32_e32 v109, v0
	v_mov_b32_e32 v110, v0
	v_mov_b32_e32 v111, v0
	v_mov_b32_e32 v116, v0
	v_mov_b32_e32 v117, v0
	v_mov_b32_e32 v118, v0
	v_mov_b32_e32 v119, v0
	v_mov_b32_e32 v120, v0
	v_mov_b32_e32 v121, v0
	v_mov_b32_e32 v122, v0
	v_mov_b32_e32 v123, v0
	v_mov_b32_e32 v124, v0
	v_mov_b32_e32 v125, v0
	v_mov_b32_e32 v126, v0
	v_mov_b32_e32 v127, v0
	v_mov_b32_e32 v32, v0
	v_mov_b32_e32 v33, v0
	v_mov_b32_e32 v34, v0
	v_mov_b32_e32 v35, v0
	v_mov_b32_e32 v28, v0
	v_mov_b32_e32 v29, v0
	v_mov_b32_e32 v30, v0
	v_mov_b32_e32 v31, v0
	v_mov_b32_e32 v12, v0
	v_mov_b32_e32 v13, v0
	v_mov_b32_e32 v14, v0
	v_mov_b32_e32 v15, v0
	v_mov_b32_e32 v8, v0
	v_mov_b32_e32 v9, v0
	v_mov_b32_e32 v10, v0
	v_mov_b32_e32 v11, v0
	v_mov_b32_e32 v64, v0
	v_mov_b32_e32 v65, v0
	v_mov_b32_e32 v66, v0
	v_mov_b32_e32 v67, v0
	v_mov_b32_e32 v60, v0
	v_mov_b32_e32 v61, v0
	v_mov_b32_e32 v62, v0
	v_mov_b32_e32 v63, v0
	v_mov_b32_e32 v52, v0
	v_mov_b32_e32 v53, v0
	v_mov_b32_e32 v54, v0
	v_mov_b32_e32 v55, v0
	v_mov_b32_e32 v48, v0
	v_mov_b32_e32 v49, v0
	v_mov_b32_e32 v50, v0
	v_mov_b32_e32 v51, v0
	v_mov_b32_e32 v44, v0
	v_mov_b32_e32 v45, v0
	v_mov_b32_e32 v46, v0
	v_mov_b32_e32 v47, v0
	v_mov_b32_e32 v40, v0
	v_mov_b32_e32 v41, v0
	v_mov_b32_e32 v42, v0
	v_mov_b32_e32 v43, v0
	v_mov_b32_e32 v20, v0
	v_mov_b32_e32 v21, v0
	v_mov_b32_e32 v22, v0
	v_mov_b32_e32 v23, v0
	v_mov_b32_e32 v16, v0
	v_mov_b32_e32 v17, v0
	v_mov_b32_e32 v18, v0
	v_mov_b32_e32 v19, v0
	v_add_u32_e32 v191, 32, v178
	v_add_u32_e32 v192, 0x10020, v178
	v_add3_u32 v194, v179, v164, 32
	v_add_u32_e32 v202, 0x10000, v194
	s_cmp_lg_u32 s28, 0
	s_mov_b32 s28, 0
	s_cbranch_scc1 .Lg0_wpre
	s_waitcnt vmcnt(8)
	s_branch .Lg0_wdone
.Lg0_wpre:
	s_waitcnt vmcnt(24)
.Lg0_wdone:
	s_barrier
	ds_read_b128 v[140:143], v194 offset:16384
	ds_read_b128 v[144:147], v194 offset:17408
	ds_read_b128 v[136:139], v194 offset:24576
	ds_read_b128 v[128:131], v194 offset:25600
	ds_read_b128 v[132:135], v191
	ds_read_b128 v[148:151], v191 offset:1024
	ds_read_b128 v[152:155], v191 offset:2048
	ds_read_b128 v[204:207], v191 offset:3072

; DI unsigned pk2(float lo, float hi) { unsigned r; asm volatile("v_cvt_pk_bf16_f32 %0, %1, %2" : "=v"(r) : "v"(lo), "v"(hi)); return r; }
; template <int MODE>
; DI void gemm_phase(const Params& p, int layer, int hf, unsigned char* shmc, int tid) {
;     ...
;     __syncthreads();
;     pre = false;
;     if (pre) {
;       gA = A + (size_t)((un.pm * BM) >> 7) * nt * 4096; gB = Bt + (size_t)((un.pn * BM) >> 7) * nt * 4096;
;       STAGE_ALL(0, 0); STAGE_ALL(1, 1);
;     }
;     const int row_b = brow + wr * 64 + fr, col_b = bcol + wc * 32 + fq * 4;
;     if (MODE == 0) {
;       if (u.pn < 26) {
;         bf16_t* proj = (bf16_t*)(wsb + WS_PROJ);
;         unsigned char* es = shmc + 65536;
; #pragma unroll
;         for (int ai = 0; ai < 2; ++ai) {
; #pragma unroll
;           for (int m = 0; m < 4; ++m) {
;             unsigned char* rp = es + (wr * 64 + m * 16 + fr) * 528 + (wc * 32 + fq * 4) * 2;
; #pragma unroll
;             for (int bj = 0; bj < 2; ++bj)
; #pragma unroll
;               for (int n = 0; n < 2; ++n) { const f32x4 v = acc[ai][bj][m][n]; uint2 w; w.x = pk2(v[0], v[1]); w.y = pk2(v[2], v[3]); *(uint2*)(rp + (bj * HALF + n * 16) * 2) = w; }
;           }
;           __syncthreads();
;           {
;             const int r0 = tid >> 5, ch = tid & 31;
; #pragma unroll
;             for (int i = 0; i < 8; ++i) {
;               const int row = r0 + 16 * i;
;               { typedef unsigned u32x4_t __attribute__((ext_vector_type(4))); const u32x4_t v_ = *(const u32x4_t*)(es + row * 528 + ch * 16); __builtin_nontemporal_store(v_, (u32x4_t*)(proj + (size_t)(brow + ai * HALF + row) * NP + bcol + ch * 8)); }
;             }
;           }
;           __syncthreads();
;         }
;       } else {
;         float* tail = (float*)(wsb + WS_TAIL);
;         float* sT = (float*)shmc;
;         if (wc == 0) {
; #pragma unroll
;           for (int ai = 0; ai < 2; ++ai)
; #pragma unroll
;             for (int m = 0; m < 4; ++m)
; #pragma unroll
;               for (int n = 0; n < 2; ++n) *(f32x4*)(sT + (ai * HALF + wr * 64 + m * 16 + fr) * 36 + n * 16 + fq * 4) = acc[ai][0][m][n];
.LBB0_168:
	s_mov_b32 s28, 0
	s_lshl_b32 s18, s27, 8
	s_cmp_gt_i32 s26, 25
	s_mov_b64 s[10:11], -1
	s_waitcnt vmcnt(0)
	s_barrier
	s_cbranch_scc0 .LBB0_179
	s_and_saveexec_b64 s[10:11], s[0:1]
	s_cbranch_execz .LBB0_171
	ds_write_b128 v188, v[124:127]
	ds_write_b128 v188, v[120:123] offset:64
	ds_write_b128 v188, v[116:119] offset:2304
	ds_write_b128 v188, v[108:111] offset:2368
	ds_write_b128 v188, v[100:103] offset:4608
	ds_write_b128 v188, v[92:95] offset:4672
	ds_write_b128 v188, v[84:87] offset:6912
	ds_write_b128 v188, v[76:79] offset:6976
	ds_write_b128 v188, v[36:39] offset:18432
	ds_write_b128 v188, v[24:27] offset:18496
	ds_write_b128 v188, v[4:7] offset:20736
	ds_write_b128 v188, v[0:3] offset:20800
	ds_write_b128 v188, v[32:35] offset:23040
	ds_write_b128 v188, v[28:31] offset:23104
	ds_write_b128 v188, v[12:15] offset:25344
	ds_write_b128 v188, v[8:11] offset:25408

; template <int MODE>
; DI void gemm_phase(const Params& p, int layer, int hf, unsigned char* shmc, int tid) {
;     ...
;     pre = false;
;     if (pre) {
;       gA = A + (size_t)((un.pm * BM) >> 7) * nt * 4096; gB = Bt + (size_t)((un.pn * BM) >> 7) * nt * 4096;
;       STAGE_ALL(0, 0); STAGE_ALL(1, 1);
;     }
.LBB0_179:
	s_and_b64 vcc, exec, s[10:11]
	s_cbranch_vccz .LBB0_153
	s_and_b64 vcc, exec, s[6:7]
	s_cbranch_vccnz .Lg0_nopre
	s_lshl_b32 s16, s25, 1
	s_ashr_i32 s17, s16, 31
	s_lshl_b64 s[16:17], s[16:17], 18
	s_add_u32 s98, s13, s16
	s_addc_u32 s99, s23, s17
	s_add_u32 s98, s98, 0xd000000
	s_addc_u32 s99, s99, 0
	s_lshl_b32 s16, s24, 1
	s_ashr_i32 s17, s16, 31
	s_lshl_b64 s[16:17], s[16:17], 18
	v_readlane_b32 s100, v254, 7
	v_readlane_b32 s101, v254, 8
	s_nop 3
	s_add_u32 s100, s100, s16
	s_addc_u32 s101, s101, s17
	s_add_u32 s100, s100, 0x11000000
	s_addc_u32 s101, s101, 0
	s_mov_b32 m0, s29
	s_add_u32 s18, s98, 0x40000
	s_addc_u32 s19, s99, 0
	global_load_lds_dwordx4 v160, s[98:99]
	s_add_u32 m0, s29, 0x4000
	s_add_u32 s16, s100, 0x40000
	s_addc_u32 s17, s101, 0
	global_load_lds_dwordx4 v160, s[100:101]
	s_add_u32 m0, s29, 0x2000
	s_add_u32 s98, s98, 0x2000
	s_addc_u32 s99, s99, 0
	global_load_lds_dwordx4 v160, s[18:19]
	s_add_u32 m0, s29, 0x6000
	s_add_u32 s100, s100, 0x2000
	s_addc_u32 s101, s101, 0
	global_load_lds_dwordx4 v160, s[16:17]
	s_add_u32 m0, s29, 0x8000
	s_add_u32 s18, s98, 0x40000
	s_addc_u32 s19, s99, 0
	global_load_lds_dwordx4 v160, s[98:99]
	s_add_u32 m0, s29, 0xc000
	s_add_u32 s16, s100, 0x40000
	s_addc_u32 s17, s101, 0
	global_load_lds_dwordx4 v160, s[100:101]
	s_add_u32 m0, s29, 0xa000
	s_add_u32 s98, s98, 0x2000
	s_addc_u32 s99, s99, 0
	global_load_lds_dwordx4 v160, s[18:19]
	s_add_u32 m0, s29, 0xe000
	s_add_u32 s100, s100, 0x2000
	s_addc_u32 s101, s101, 0
	global_load_lds_dwordx4 v160, s[16:17]
	s_mov_b32 s28, 1
	s_lshl_b32 s18, s27, 8
; DI unsigned pk2(float lo, float hi) { unsigned r; asm volatile("v_cvt_pk_bf16_f32 %0, %1, %2" : "=v"(r) : "v"(lo), "v"(hi)); return r; }
; template <int MODE>
; DI void gemm_phase(const Params& p, int layer, int hf, unsigned char* shmc, int tid) {
;     ...
;     const int row_b = brow + wr * 64 + fr, col_b = bcol + wc * 32 + fq * 4;
;     if (MODE == 0) {
;       if (u.pn < 26) {
;         bf16_t* proj = (bf16_t*)(wsb + WS_PROJ);
;         unsigned char* es = shmc + 65536;
; #pragma unroll
;         for (int ai = 0; ai < 2; ++ai) {
; #pragma unroll
;           for (int m = 0; m < 4; ++m) {
;             unsigned char* rp = es + (wr * 64 + m * 16 + fr) * 528 + (wc * 32 + fq * 4) * 2;
; #pragma unroll
;             for (int bj = 0; bj < 2; ++bj)
; #pragma unroll
;               for (int n = 0; n < 2; ++n) { const f32x4 v = acc[ai][bj][m][n]; uint2 w; w.x = pk2(v[0], v[1]); w.y = pk2(v[2], v[3]); *(uint2*)(rp + (bj * HALF + n * 16) * 2) = w; }
;           }
;           __syncthreads();
;           {
;             const int r0 = tid >> 5, ch = tid & 31;
; #pragma unroll
;             for (int i = 0; i < 8; ++i) {
;               const int row = r0 + 16 * i;
;               { typedef unsigned u32x4_t __attribute__((ext_vector_type(4))); const u32x4_t v_ = *(const u32x4_t*)(es + row * 528 + ch * 16); __builtin_nontemporal_store(v_, (u32x4_t*)(proj + (size_t)(brow + ai * HALF + row) * NP + bcol + ch * 8)); }
;             }
;           }
;           __syncthreads();
;         }
.Lg0_nopre:
	v_cvt_pk_bf16_f32 v124, v124, v125
	v_cvt_pk_bf16_f32 v125, v126, v127
	ds_write_b64 v189, v[124:125]
	v_cvt_pk_bf16_f32 v120, v120, v121
	v_cvt_pk_bf16_f32 v121, v122, v123
	ds_write_b64 v189, v[120:121] offset:32
	v_cvt_pk_bf16_f32 v112, v112, v113
	v_cvt_pk_bf16_f32 v113, v114, v115
	ds_write_b64 v189, v[112:113] offset:256
	v_cvt_pk_bf16_f32 v104, v104, v105
	v_cvt_pk_bf16_f32 v105, v106, v107
	ds_write_b64 v189, v[104:105] offset:288
	v_cvt_pk_bf16_f32 v104, v116, v117
	v_cvt_pk_bf16_f32 v105, v118, v119
	ds_write_b64 v189, v[104:105] offset:8448
	v_cvt_pk_bf16_f32 v104, v108, v109
	v_cvt_pk_bf16_f32 v105, v110, v111
	ds_write_b64 v189, v[104:105] offset:8480
	v_cvt_pk_bf16_f32 v96, v96, v97
	v_cvt_pk_bf16_f32 v97, v98, v99
	ds_write_b64 v189, v[96:97] offset:8704
	v_cvt_pk_bf16_f32 v88, v88, v89
	v_cvt_pk_bf16_f32 v89, v90, v91
	ds_write_b64 v189, v[88:89] offset:8736
	v_cvt_pk_bf16_f32 v88, v100, v101
	v_cvt_pk_bf16_f32 v89, v102, v103
	ds_write_b64 v189, v[88:89] offset:16896
	v_cvt_pk_bf16_f32 v88, v92, v93
	v_cvt_pk_bf16_f32 v89, v94, v95
	ds_write_b64 v189, v[88:89] offset:16928
	v_cvt_pk_bf16_f32 v80, v80, v81
	v_cvt_pk_bf16_f32 v81, v82, v83
	ds_write_b64 v189, v[80:81] offset:17152
	v_cvt_pk_bf16_f32 v72, v72, v73
	v_cvt_pk_bf16_f32 v73, v74, v75
	ds_write_b64 v189, v[72:73] offset:17184
	v_cvt_pk_bf16_f32 v72, v84, v85
	v_cvt_pk_bf16_f32 v73, v86, v87
	s_lshl_b32 s10, s26, 8
	ds_write_b64 v189, v[72:73] offset:25344
	v_cvt_pk_bf16_f32 v72, v76, v77
	v_cvt_pk_bf16_f32 v73, v78, v79
	ds_write_b64 v189, v[72:73] offset:25376
	v_cvt_pk_bf16_f32 v68, v68, v69
	v_cvt_pk_bf16_f32 v69, v70, v71
	ds_write_b64 v189, v[68:69] offset:25600
	v_cvt_pk_bf16_f32 v56, v56, v57
	v_cvt_pk_bf16_f32 v57, v58, v59
	s_ashr_i32 s11, s10, 31
	ds_write_b64 v189, v[56:57] offset:25632
	s_waitcnt lgkmcnt(0)
	s_barrier
	ds_read_b128 v[56:59], v190
	v_lshl_add_u64 v[128:129], s[10:11], 1, v[174:175]
	v_add_u32_e32 v68, s18, v180
	v_mad_i64_i32 v[72:73], s[10:11], v68, s65, v[128:129]
	ds_read_b128 v[68:71], v190 offset:8448
	s_waitcnt lgkmcnt(1)
	global_store_dwordx4 v[72:73], v[56:59], off nt
	s_nop 1
	v_add_u32_e32 v56, s18, v181
	v_mad_i64_i32 v[56:57], s[10:11], v56, s65, v[128:129]
	s_waitcnt lgkmcnt(0)
	global_store_dwordx4 v[56:57], v[68:71], off nt
	ds_read_b128 v[56:59], v190 offset:16896
	s_nop 0
	v_add_u32_e32 v68, s18, v182
	v_mad_i64_i32 v[72:73], s[10:11], v68, s65, v[128:129]
	ds_read_b128 v[68:71], v190 offset:25344
	s_waitcnt lgkmcnt(1)
	global_store_dwordx4 v[72:73], v[56:59], off nt
	s_nop 1
	v_add_u32_e32 v56, s18, v183
	v_mad_i64_i32 v[56:57], s[10:11], v56, s65, v[128:129]
	s_waitcnt lgkmcnt(0)
	global_store_dwordx4 v[56:57], v[68:71], off nt
	ds_read_b128 v[56:59], v190 offset:33792
	s_nop 0
	v_add_u32_e32 v68, s18, v184
	v_mad_i64_i32 v[72:73], s[10:11], v68, s65, v[128:129]
	ds_read_b128 v[68:71], v190 offset:42240
	s_waitcnt lgkmcnt(1)
	global_store_dwordx4 v[72:73], v[56:59], off nt
	s_nop 1
	v_add_u32_e32 v56, s18, v185
	v_mad_i64_i32 v[56:57], s[10:11], v56, s65, v[128:129]
	s_waitcnt lgkmcnt(0)
	global_store_dwordx4 v[56:57], v[68:71], off nt
	ds_read_b128 v[56:59], v190 offset:50688
	s_nop 0
	v_add_u32_e32 v68, s18, v186
	v_mad_i64_i32 v[72:73], s[10:11], v68, s65, v[128:129]
	ds_read_b128 v[68:71], v190 offset:59136
	s_waitcnt lgkmcnt(1)
	global_store_dwordx4 v[72:73], v[56:59], off nt
	s_nop 1
	v_add_u32_e32 v56, s18, v187
	v_mad_i64_i32 v[56:57], s[10:11], v56, s65, v[128:129]
	s_waitcnt lgkmcnt(0)
	global_store_dwordx4 v[56:57], v[68:71], off nt
	s_barrier
	v_cvt_pk_bf16_f32 v36, v36, v37
	v_cvt_pk_bf16_f32 v37, v38, v39
	ds_write_b64 v189, v[36:37]
	v_cvt_pk_bf16_f32 v24, v24, v25
	v_cvt_pk_bf16_f32 v25, v26, v27
	ds_write_b64 v189, v[24:25] offset:32
	v_cvt_pk_bf16_f32 v24, v64, v65
	v_cvt_pk_bf16_f32 v25, v66, v67
	ds_write_b64 v189, v[24:25] offset:256
	v_cvt_pk_bf16_f32 v24, v60, v61
	v_cvt_pk_bf16_f32 v25, v62, v63
	ds_write_b64 v189, v[24:25] offset:288
	v_cvt_pk_bf16_f32 v4, v4, v5
	v_cvt_pk_bf16_f32 v5, v6, v7
	ds_write_b64 v189, v[4:5] offset:8448
	v_cvt_pk_bf16_f32 v0, v0, v1
	v_cvt_pk_bf16_f32 v1, v2, v3
	ds_write_b64 v189, v[0:1] offset:8480
	v_cvt_pk_bf16_f32 v0, v52, v53
	v_cvt_pk_bf16_f32 v1, v54, v55
	ds_write_b64 v189, v[0:1] offset:8704
	v_cvt_pk_bf16_f32 v0, v48, v49
	v_cvt_pk_bf16_f32 v1, v50, v51
	ds_write_b64 v189, v[0:1] offset:8736
	v_cvt_pk_bf16_f32 v0, v32, v33
	v_cvt_pk_bf16_f32 v1, v34, v35
	ds_write_b64 v189, v[0:1] offset:16896
	v_cvt_pk_bf16_f32 v0, v28, v29
	v_cvt_pk_bf16_f32 v1, v30, v31
	ds_write_b64 v189, v[0:1] offset:16928
	v_cvt_pk_bf16_f32 v0, v44, v45
	v_cvt_pk_bf16_f32 v1, v46, v47
	ds_write_b64 v189, v[0:1] offset:17152
	v_cvt_pk_bf16_f32 v0, v40, v41
	v_cvt_pk_bf16_f32 v1, v42, v43
	ds_write_b64 v189, v[0:1] offset:17184
	v_cvt_pk_bf16_f32 v0, v12, v13
	v_cvt_pk_bf16_f32 v1, v14, v15
	ds_write_b64 v189, v[0:1] offset:25344
	v_cvt_pk_bf16_f32 v0, v8, v9
	v_cvt_pk_bf16_f32 v1, v10, v11
	ds_write_b64 v189, v[0:1] offset:25376
	v_cvt_pk_bf16_f32 v0, v20, v21
	v_cvt_pk_bf16_f32 v1, v22, v23
	ds_write_b64 v189, v[0:1] offset:25600
	v_cvt_pk_bf16_f32 v0, v16, v17
	v_cvt_pk_bf16_f32 v1, v18, v19
	ds_write_b64 v189, v[0:1] offset:25632
	s_waitcnt lgkmcnt(0)
	s_barrier
	s_bitset1_b32 s18, 7
	ds_read_b128 v[0:3], v190
	v_add_u32_e32 v4, s18, v180
	v_mad_i64_i32 v[8:9], s[10:11], v4, s65, v[128:129]
	ds_read_b128 v[4:7], v190 offset:8448
	s_waitcnt lgkmcnt(1)
	global_store_dwordx4 v[8:9], v[0:3], off nt
	s_nop 1
	v_add_u32_e32 v0, s18, v181
	v_mad_i64_i32 v[0:1], s[10:11], v0, s65, v[128:129]
	s_waitcnt lgkmcnt(0)
	global_store_dwordx4 v[0:1], v[4:7], off nt
	ds_read_b128 v[0:3], v190 offset:16896
	s_nop 0
	v_add_u32_e32 v4, s18, v182
	v_mad_i64_i32 v[8:9], s[10:11], v4, s65, v[128:129]
	ds_read_b128 v[4:7], v190 offset:25344
	s_waitcnt lgkmcnt(1)
	global_store_dwordx4 v[8:9], v[0:3], off nt
	s_nop 1
	v_add_u32_e32 v0, s18, v183
	v_mad_i64_i32 v[0:1], s[10:11], v0, s65, v[128:129]
	s_waitcnt lgkmcnt(0)
	global_store_dwordx4 v[0:1], v[4:7], off nt
	ds_read_b128 v[0:3], v190 offset:33792
	s_nop 0
	v_add_u32_e32 v4, s18, v184
	v_mad_i64_i32 v[8:9], s[10:11], v4, s65, v[128:129]
	ds_read_b128 v[4:7], v190 offset:42240
	s_waitcnt lgkmcnt(1)
	global_store_dwordx4 v[8:9], v[0:3], off nt
	s_nop 1
	v_add_u32_e32 v0, s18, v185
	v_mad_i64_i32 v[0:1], s[10:11], v0, s65, v[128:129]
	s_waitcnt lgkmcnt(0)
	global_store_dwordx4 v[0:1], v[4:7], off nt
	ds_read_b128 v[0:3], v190 offset:50688
	s_nop 0
	v_add_u32_e32 v4, s18, v186
	v_mad_i64_i32 v[8:9], s[10:11], v4, s65, v[128:129]
	ds_read_b128 v[4:7], v190 offset:59136
	s_waitcnt lgkmcnt(1)
	global_store_dwordx4 v[8:9], v[0:3], off nt
	s_nop 1
	v_add_u32_e32 v0, s18, v187
	v_mad_i64_i32 v[0:1], s[10:11], v0, s65, v[128:129]
	s_waitcnt lgkmcnt(0)
	global_store_dwordx4 v[0:1], v[4:7], off nt
	s_barrier
	s_branch .LBB0_153
